# scan consumer: pa-dot and y-dot issued before the LDS read burst (burst off the S chain head)
# speedup vs baseline: 1.0114x; 1.0114x over previous
; template <int CTRL> __device__ __forceinline__ float dpp_f(float x) { return __int_as_float(__builtin_amdgcn_update_dpp(0, __float_as_int(x), CTRL, 0xf, 0xf, false)); }
; __device__ __forceinline__ void p8_scan(const Args& a, LAS unsigned char* lds) {
;     ...
;                 for (int tt = 0; tt < TC; ++tt) {
;                     ScanOps n; scan_ld(n, bt + (tt + 1 < TC ? tt + 1 : tt) * SPITCH, jq4, myrow);
;                     __builtin_amdgcn_sched_barrier(0);
;                     f32x2 ta = S01 * o.al.lo, ty = S01 * o.wr.lo; ta = S23 * o.al.hi + ta; ty = S23 * o.wr.hi + ty;
;                     float pa = ta.x + ta.y, py = ty.x + ty.y;
;                     f32x2 kv01 = o.kv.lo * o.vi, kv23 = o.kv.hi * o.vi;
;     ...
;                     asm volatile("" : "+v"(kv01), "+v"(kv23), "+v"(vc));
;                     pa += dpp_f<0x121>(pa); py += dpp_f<0x121>(py); pa += dpp_f<0x122>(pa); py += dpp_f<0x122>(py);
;                     pa += dpp_f<0x124>(pa); pa += dpp_f<0x128>(pa);
;                     S01 = S01 * o.wv.lo + (o.be.lo * pa + kv01);
;                     S23 = S23 * o.wv.hi + (o.be.hi * pa + kv23);
;     ...
;                     __builtin_amdgcn_sched_barrier(0);
;                     o = n;
;                 }
.LBB0_1090:
	s_and_b32 s43, s14, 1
	s_mul_i32 s52, s43, 0xc400
	s_lshl_b32 s43, s43, 13
	v_lshl_add_u32 v38, v27, 2, s52
	v_lshl_add_u32 v39, v1, 2, s52
	v_mov_b32_e32 v40, s52
	v_add_u32_e32 v41, s43, v123
	v_cndmask_b32_e64 v41, v124, v41, s[2:3]
	ds_read_b128 v[10:13], v38 offset:512
	ds_read_b128 v[6:9], v38 offset:256
	ds_read_b32 v28, v39 offset:1280
	ds_read_b128 v[2:5], v38 offset:0
	ds_read_b128 v[14:17], v38 offset:768
	ds_read_b128 v[18:21], v38 offset:1024
	s_waitcnt lgkmcnt(3)
	v_pk_mul_f32 v[34:35], v[22:23], v[10:11]
	v_pk_fma_f32 v[34:35], v[24:25], v[12:13], v[34:35]
	ds_read_b128 v[50:53], v38 offset:2080
	ds_read_b128 v[46:49], v38 offset:1824
	ds_read_b32 v62, v39 offset:2848
	ds_read_b128 v[42:45], v38 offset:1568
	ds_read_b128 v[54:57], v38 offset:2336
	ds_read_b128 v[58:61], v38 offset:2592
	v_add_f32_e32 v34, v34, v35
	v_pk_mul_f32 v[6:7], v[6:7], v[28:29] op_sel_hi:[1,0]
	v_pk_mul_f32 v[8:9], v[8:9], v[28:29] op_sel_hi:[1,0]
	v_add_f32_dpp v34, v34, v34 row_ror:1 row_mask:0xf bank_mask:0xf bound_ctrl:1
	s_waitcnt lgkmcnt(7)
	v_pk_fma_f32 v[6:7], v[22:23], v[2:3], v[6:7]
	v_pk_fma_f32 v[8:9], v[24:25], v[4:5], v[8:9]
	v_add_f32_dpp v34, v34, v34 row_ror:2 row_mask:0xf bank_mask:0xf bound_ctrl:1
	s_nop 0
	s_nop 0
	v_add_f32_dpp v34, v34, v34 row_ror:4 row_mask:0xf bank_mask:0xf bound_ctrl:1
	s_nop 0
	s_nop 0
	v_add_f32_dpp v34, v34, v34 row_ror:8 row_mask:0xf bank_mask:0xf bound_ctrl:1
	v_pk_fma_f32 v[22:23], v[14:15], v[34:35], v[6:7] op_sel_hi:[1,0,1]
	v_pk_fma_f32 v[24:25], v[16:17], v[34:35], v[8:9] op_sel_hi:[1,0,1]
	s_waitcnt lgkmcnt(3)
	v_pk_mul_f32 v[34:35], v[22:23], v[50:51]
	v_pk_mul_f32 v[36:37], v[22:23], v[18:19]
	v_pk_fma_f32 v[34:35], v[24:25], v[52:53], v[34:35]
	v_pk_fma_f32 v[36:37], v[24:25], v[20:21], v[36:37]
	ds_read_b128 v[10:13], v38 offset:3648
	ds_read_b128 v[6:9], v38 offset:3392
	ds_read_b32 v28, v39 offset:4416
	ds_read_b128 v[2:5], v38 offset:3136
	ds_read_b128 v[14:17], v38 offset:3904
	ds_read_b128 v[18:21], v38 offset:4160
	v_add_f32_e32 v34, v34, v35
	v_add_f32_e32 v36, v36, v37
	v_pk_mul_f32 v[46:47], v[46:47], v[62:63] op_sel_hi:[1,0]
	v_add_f32_dpp v34, v34, v34 row_ror:1 row_mask:0xf bank_mask:0xf bound_ctrl:1
	v_add_f32_dpp v36, v36, v36 row_ror:1 row_mask:0xf bank_mask:0xf bound_ctrl:1
	s_waitcnt lgkmcnt(7)
	v_pk_fma_f32 v[46:47], v[22:23], v[42:43], v[46:47]
	v_add_f32_dpp v34, v34, v34 row_ror:2 row_mask:0xf bank_mask:0xf bound_ctrl:1
	v_add_f32_dpp v36, v36, v36 row_ror:2 row_mask:0xf bank_mask:0xf bound_ctrl:1
	v_pk_mul_f32 v[48:49], v[48:49], v[62:63] op_sel_hi:[1,0]
	v_add_f32_dpp v34, v34, v34 row_ror:4 row_mask:0xf bank_mask:0xf bound_ctrl:1
	v_pk_fma_f32 v[48:49], v[24:25], v[44:45], v[48:49]
	s_nop 0
	v_add_f32_dpp v34, v34, v34 row_ror:8 row_mask:0xf bank_mask:0xf bound_ctrl:1
	v_pk_fma_f32 v[22:23], v[54:55], v[34:35], v[46:47] op_sel_hi:[1,0,1]
	v_pk_fma_f32 v[24:25], v[56:57], v[34:35], v[48:49] op_sel_hi:[1,0,1]
	s_waitcnt lgkmcnt(3)
	v_pk_mul_f32 v[34:35], v[22:23], v[10:11]
	v_pk_mul_f32 v[66:67], v[22:23], v[58:59]
	v_pk_fma_f32 v[34:35], v[24:25], v[12:13], v[34:35]
	v_pk_fma_f32 v[66:67], v[24:25], v[60:61], v[66:67]
	ds_read_b128 v[50:53], v38 offset:5216
	ds_read_b128 v[46:49], v38 offset:4960
	ds_read_b32 v62, v39 offset:5984
	ds_read_b128 v[42:45], v38 offset:4704
	ds_read_b128 v[54:57], v38 offset:5472
	ds_read_b128 v[58:61], v38 offset:5728
	v_add_f32_e32 v34, v34, v35
	v_add_f32_e32 v66, v66, v67
	v_pk_mul_f32 v[6:7], v[6:7], v[28:29] op_sel_hi:[1,0]
	v_add_f32_dpp v34, v34, v34 row_ror:1 row_mask:0xf bank_mask:0xf bound_ctrl:1
	v_add_f32_dpp v66, v66, v66 row_ror:1 row_mask:0xf bank_mask:0xf bound_ctrl:1
	s_waitcnt lgkmcnt(7)
	v_pk_fma_f32 v[6:7], v[22:23], v[2:3], v[6:7]
	v_add_f32_dpp v34, v34, v34 row_ror:2 row_mask:0xf bank_mask:0xf bound_ctrl:1
	v_add_f32_dpp v66, v66, v66 row_ror:2 row_mask:0xf bank_mask:0xf bound_ctrl:1
	v_pk_mul_f32 v[8:9], v[8:9], v[28:29] op_sel_hi:[1,0]
	v_add_f32_dpp v34, v34, v34 row_ror:4 row_mask:0xf bank_mask:0xf bound_ctrl:1
	v_pk_fma_f32 v[8:9], v[24:25], v[4:5], v[8:9]
	ds_write2st64_b32 v41, v36, v66 offset0:0 offset1:1
	v_add_f32_dpp v34, v34, v34 row_ror:8 row_mask:0xf bank_mask:0xf bound_ctrl:1
	v_pk_fma_f32 v[22:23], v[14:15], v[34:35], v[6:7] op_sel_hi:[1,0,1]
	v_pk_fma_f32 v[24:25], v[16:17], v[34:35], v[8:9] op_sel_hi:[1,0,1]
	s_waitcnt lgkmcnt(4)
	v_pk_mul_f32 v[34:35], v[22:23], v[50:51]
	v_pk_mul_f32 v[36:37], v[22:23], v[18:19]
	v_pk_fma_f32 v[34:35], v[24:25], v[52:53], v[34:35]
	v_pk_fma_f32 v[36:37], v[24:25], v[20:21], v[36:37]
	ds_read_b128 v[10:13], v38 offset:6784
	ds_read_b128 v[6:9], v38 offset:6528
	ds_read_b32 v28, v39 offset:7552
	ds_read_b128 v[2:5], v38 offset:6272
	ds_read_b128 v[14:17], v38 offset:7040
	ds_read_b128 v[18:21], v38 offset:7296
	v_add_f32_e32 v34, v34, v35
	v_add_f32_e32 v36, v36, v37
	v_pk_mul_f32 v[46:47], v[46:47], v[62:63] op_sel_hi:[1,0]
	v_add_f32_dpp v34, v34, v34 row_ror:1 row_mask:0xf bank_mask:0xf bound_ctrl:1
	v_add_f32_dpp v36, v36, v36 row_ror:1 row_mask:0xf bank_mask:0xf bound_ctrl:1
	s_waitcnt lgkmcnt(8)
	v_pk_fma_f32 v[46:47], v[22:23], v[42:43], v[46:47]
	v_add_f32_dpp v34, v34, v34 row_ror:2 row_mask:0xf bank_mask:0xf bound_ctrl:1
	v_add_f32_dpp v36, v36, v36 row_ror:2 row_mask:0xf bank_mask:0xf bound_ctrl:1
	v_pk_mul_f32 v[48:49], v[48:49], v[62:63] op_sel_hi:[1,0]
	v_add_f32_dpp v34, v34, v34 row_ror:4 row_mask:0xf bank_mask:0xf bound_ctrl:1
	v_pk_fma_f32 v[48:49], v[24:25], v[44:45], v[48:49]
	s_nop 0
	v_add_f32_dpp v34, v34, v34 row_ror:8 row_mask:0xf bank_mask:0xf bound_ctrl:1
	v_pk_fma_f32 v[22:23], v[54:55], v[34:35], v[46:47] op_sel_hi:[1,0,1]
	v_pk_fma_f32 v[24:25], v[56:57], v[34:35], v[48:49] op_sel_hi:[1,0,1]
	s_waitcnt lgkmcnt(3)
; template <int CTRL> __device__ __forceinline__ float dpp_f(float x) { return __int_as_float(__builtin_amdgcn_update_dpp(0, __float_as_int(x), CTRL, 0xf, 0xf, false)); }
; __device__ __forceinline__ void p8_scan(const Args& a, LAS unsigned char* lds) {
;     ...
;                 for (int tt = 0; tt < TC; ++tt) {
;                     ScanOps n; scan_ld(n, bt + (tt + 1 < TC ? tt + 1 : tt) * SPITCH, jq4, myrow);
;                     __builtin_amdgcn_sched_barrier(0);
;                     f32x2 ta = S01 * o.al.lo, ty = S01 * o.wr.lo; ta = S23 * o.al.hi + ta; ty = S23 * o.wr.hi + ty;
;                     float pa = ta.x + ta.y, py = ty.x + ty.y;
;                     f32x2 kv01 = o.kv.lo * o.vi, kv23 = o.kv.hi * o.vi;
;     ...
;                     asm volatile("" : "+v"(kv01), "+v"(kv23), "+v"(vc));
;                     pa += dpp_f<0x121>(pa); py += dpp_f<0x121>(py); pa += dpp_f<0x122>(pa); py += dpp_f<0x122>(py);
;                     pa += dpp_f<0x124>(pa); pa += dpp_f<0x128>(pa);
;                     S01 = S01 * o.wv.lo + (o.be.lo * pa + kv01);
;                     S23 = S23 * o.wv.hi + (o.be.hi * pa + kv23);
;     ...
;                     __builtin_amdgcn_sched_barrier(0);
;                     o = n;
;                 }
	v_pk_mul_f32 v[34:35], v[22:23], v[10:11]
	v_pk_mul_f32 v[66:67], v[22:23], v[58:59]
	v_pk_fma_f32 v[34:35], v[24:25], v[12:13], v[34:35]
	v_pk_fma_f32 v[66:67], v[24:25], v[60:61], v[66:67]
	ds_read_b128 v[50:53], v38 offset:8352
	ds_read_b128 v[46:49], v38 offset:8096
	ds_read_b32 v62, v39 offset:9120
	ds_read_b128 v[42:45], v38 offset:7840
	ds_read_b128 v[54:57], v38 offset:8608
	ds_read_b128 v[58:61], v38 offset:8864
	v_add_f32_e32 v34, v34, v35
	v_add_f32_e32 v66, v66, v67
	v_pk_mul_f32 v[6:7], v[6:7], v[28:29] op_sel_hi:[1,0]
	v_add_f32_dpp v34, v34, v34 row_ror:1 row_mask:0xf bank_mask:0xf bound_ctrl:1
	v_add_f32_dpp v66, v66, v66 row_ror:1 row_mask:0xf bank_mask:0xf bound_ctrl:1
	s_waitcnt lgkmcnt(7)
	v_pk_fma_f32 v[6:7], v[22:23], v[2:3], v[6:7]
	v_add_f32_dpp v34, v34, v34 row_ror:2 row_mask:0xf bank_mask:0xf bound_ctrl:1
	v_add_f32_dpp v66, v66, v66 row_ror:2 row_mask:0xf bank_mask:0xf bound_ctrl:1
	v_pk_mul_f32 v[8:9], v[8:9], v[28:29] op_sel_hi:[1,0]
	v_add_f32_dpp v34, v34, v34 row_ror:4 row_mask:0xf bank_mask:0xf bound_ctrl:1
	v_pk_fma_f32 v[8:9], v[24:25], v[4:5], v[8:9]
	ds_write2st64_b32 v41, v36, v66 offset0:2 offset1:3
	v_add_f32_dpp v34, v34, v34 row_ror:8 row_mask:0xf bank_mask:0xf bound_ctrl:1
	v_pk_fma_f32 v[22:23], v[14:15], v[34:35], v[6:7] op_sel_hi:[1,0,1]
	v_pk_fma_f32 v[24:25], v[16:17], v[34:35], v[8:9] op_sel_hi:[1,0,1]
	s_waitcnt lgkmcnt(4)
	v_pk_mul_f32 v[34:35], v[22:23], v[50:51]
	v_pk_mul_f32 v[36:37], v[22:23], v[18:19]
	v_pk_fma_f32 v[34:35], v[24:25], v[52:53], v[34:35]
	v_pk_fma_f32 v[36:37], v[24:25], v[20:21], v[36:37]
	ds_read_b128 v[10:13], v38 offset:9920
	ds_read_b128 v[6:9], v38 offset:9664
	ds_read_b32 v28, v39 offset:10688
	ds_read_b128 v[2:5], v38 offset:9408
	ds_read_b128 v[14:17], v38 offset:10176
	ds_read_b128 v[18:21], v38 offset:10432
	v_add_f32_e32 v34, v34, v35
	v_add_f32_e32 v36, v36, v37
	v_pk_mul_f32 v[46:47], v[46:47], v[62:63] op_sel_hi:[1,0]
	v_add_f32_dpp v34, v34, v34 row_ror:1 row_mask:0xf bank_mask:0xf bound_ctrl:1
	v_add_f32_dpp v36, v36, v36 row_ror:1 row_mask:0xf bank_mask:0xf bound_ctrl:1
	s_waitcnt lgkmcnt(8)
	v_pk_fma_f32 v[46:47], v[22:23], v[42:43], v[46:47]
	v_add_f32_dpp v34, v34, v34 row_ror:2 row_mask:0xf bank_mask:0xf bound_ctrl:1
	v_add_f32_dpp v36, v36, v36 row_ror:2 row_mask:0xf bank_mask:0xf bound_ctrl:1
	v_pk_mul_f32 v[48:49], v[48:49], v[62:63] op_sel_hi:[1,0]
	v_add_f32_dpp v34, v34, v34 row_ror:4 row_mask:0xf bank_mask:0xf bound_ctrl:1
	v_pk_fma_f32 v[48:49], v[24:25], v[44:45], v[48:49]
	s_nop 0
	v_add_f32_dpp v34, v34, v34 row_ror:8 row_mask:0xf bank_mask:0xf bound_ctrl:1
	v_pk_fma_f32 v[22:23], v[54:55], v[34:35], v[46:47] op_sel_hi:[1,0,1]
	v_pk_fma_f32 v[24:25], v[56:57], v[34:35], v[48:49] op_sel_hi:[1,0,1]
	s_waitcnt lgkmcnt(3)
	v_pk_mul_f32 v[34:35], v[22:23], v[10:11]
	v_pk_mul_f32 v[66:67], v[22:23], v[58:59]
	v_pk_fma_f32 v[34:35], v[24:25], v[12:13], v[34:35]
	v_pk_fma_f32 v[66:67], v[24:25], v[60:61], v[66:67]
	ds_read_b128 v[50:53], v38 offset:11488
	ds_read_b128 v[46:49], v38 offset:11232
	ds_read_b32 v62, v39 offset:12256
	ds_read_b128 v[42:45], v38 offset:10976
	ds_read_b128 v[54:57], v38 offset:11744
	ds_read_b128 v[58:61], v38 offset:12000
	v_add_f32_e32 v34, v34, v35
	v_add_f32_e32 v66, v66, v67
	v_pk_mul_f32 v[6:7], v[6:7], v[28:29] op_sel_hi:[1,0]
	v_add_f32_dpp v34, v34, v34 row_ror:1 row_mask:0xf bank_mask:0xf bound_ctrl:1
	v_add_f32_dpp v66, v66, v66 row_ror:1 row_mask:0xf bank_mask:0xf bound_ctrl:1
	s_waitcnt lgkmcnt(7)
	v_pk_fma_f32 v[6:7], v[22:23], v[2:3], v[6:7]
	v_add_f32_dpp v34, v34, v34 row_ror:2 row_mask:0xf bank_mask:0xf bound_ctrl:1
	v_add_f32_dpp v66, v66, v66 row_ror:2 row_mask:0xf bank_mask:0xf bound_ctrl:1
	v_pk_mul_f32 v[8:9], v[8:9], v[28:29] op_sel_hi:[1,0]
	v_add_f32_dpp v34, v34, v34 row_ror:4 row_mask:0xf bank_mask:0xf bound_ctrl:1
	v_pk_fma_f32 v[8:9], v[24:25], v[4:5], v[8:9]
	ds_write2st64_b32 v41, v36, v66 offset0:4 offset1:5
	v_add_f32_dpp v34, v34, v34 row_ror:8 row_mask:0xf bank_mask:0xf bound_ctrl:1
	v_pk_fma_f32 v[22:23], v[14:15], v[34:35], v[6:7] op_sel_hi:[1,0,1]
	v_pk_fma_f32 v[24:25], v[16:17], v[34:35], v[8:9] op_sel_hi:[1,0,1]
	s_waitcnt lgkmcnt(4)
	v_pk_mul_f32 v[34:35], v[22:23], v[50:51]
	v_pk_mul_f32 v[36:37], v[22:23], v[18:19]
	v_pk_fma_f32 v[34:35], v[24:25], v[52:53], v[34:35]
	v_pk_fma_f32 v[36:37], v[24:25], v[20:21], v[36:37]
	ds_read_b128 v[10:13], v38 offset:13056
	ds_read_b128 v[6:9], v38 offset:12800
	ds_read_b32 v28, v39 offset:13824
	ds_read_b128 v[2:5], v38 offset:12544
	ds_read_b128 v[14:17], v38 offset:13312
	ds_read_b128 v[18:21], v38 offset:13568
	v_add_f32_e32 v34, v34, v35
	v_add_f32_e32 v36, v36, v37
	v_pk_mul_f32 v[46:47], v[46:47], v[62:63] op_sel_hi:[1,0]
	v_add_f32_dpp v34, v34, v34 row_ror:1 row_mask:0xf bank_mask:0xf bound_ctrl:1
	v_add_f32_dpp v36, v36, v36 row_ror:1 row_mask:0xf bank_mask:0xf bound_ctrl:1
	s_waitcnt lgkmcnt(8)
	v_pk_fma_f32 v[46:47], v[22:23], v[42:43], v[46:47]
	v_add_f32_dpp v34, v34, v34 row_ror:2 row_mask:0xf bank_mask:0xf bound_ctrl:1
	v_add_f32_dpp v36, v36, v36 row_ror:2 row_mask:0xf bank_mask:0xf bound_ctrl:1
	v_pk_mul_f32 v[48:49], v[48:49], v[62:63] op_sel_hi:[1,0]
	v_add_f32_dpp v34, v34, v34 row_ror:4 row_mask:0xf bank_mask:0xf bound_ctrl:1
	v_pk_fma_f32 v[48:49], v[24:25], v[44:45], v[48:49]
	s_nop 0
	v_add_f32_dpp v34, v34, v34 row_ror:8 row_mask:0xf bank_mask:0xf bound_ctrl:1
	v_pk_fma_f32 v[22:23], v[54:55], v[34:35], v[46:47] op_sel_hi:[1,0,1]
	v_pk_fma_f32 v[24:25], v[56:57], v[34:35], v[48:49] op_sel_hi:[1,0,1]
	s_waitcnt lgkmcnt(3)
; template <int CTRL> __device__ __forceinline__ float dpp_f(float x) { return __int_as_float(__builtin_amdgcn_update_dpp(0, __float_as_int(x), CTRL, 0xf, 0xf, false)); }
; __device__ __forceinline__ void p8_scan(const Args& a, LAS unsigned char* lds) {
;     ...
;                 for (int tt = 0; tt < TC; ++tt) {
;                     ScanOps n; scan_ld(n, bt + (tt + 1 < TC ? tt + 1 : tt) * SPITCH, jq4, myrow);
;                     __builtin_amdgcn_sched_barrier(0);
;                     f32x2 ta = S01 * o.al.lo, ty = S01 * o.wr.lo; ta = S23 * o.al.hi + ta; ty = S23 * o.wr.hi + ty;
;                     float pa = ta.x + ta.y, py = ty.x + ty.y;
;                     f32x2 kv01 = o.kv.lo * o.vi, kv23 = o.kv.hi * o.vi;
;     ...
;                     asm volatile("" : "+v"(kv01), "+v"(kv23), "+v"(vc));
;                     pa += dpp_f<0x121>(pa); py += dpp_f<0x121>(py); pa += dpp_f<0x122>(pa); py += dpp_f<0x122>(py);
;                     pa += dpp_f<0x124>(pa); pa += dpp_f<0x128>(pa);
;                     S01 = S01 * o.wv.lo + (o.be.lo * pa + kv01);
;                     S23 = S23 * o.wv.hi + (o.be.hi * pa + kv23);
;     ...
;                     __builtin_amdgcn_sched_barrier(0);
;                     o = n;
;                 }
	v_pk_mul_f32 v[34:35], v[22:23], v[10:11]
	v_pk_mul_f32 v[66:67], v[22:23], v[58:59]
	v_pk_fma_f32 v[34:35], v[24:25], v[12:13], v[34:35]
	v_pk_fma_f32 v[66:67], v[24:25], v[60:61], v[66:67]
	ds_read_b128 v[50:53], v38 offset:14624
	ds_read_b128 v[46:49], v38 offset:14368
	ds_read_b32 v62, v39 offset:15392
	ds_read_b128 v[42:45], v38 offset:14112
	ds_read_b128 v[54:57], v38 offset:14880
	ds_read_b128 v[58:61], v38 offset:15136
	v_add_f32_e32 v34, v34, v35
	v_add_f32_e32 v66, v66, v67
	v_pk_mul_f32 v[6:7], v[6:7], v[28:29] op_sel_hi:[1,0]
	v_add_f32_dpp v34, v34, v34 row_ror:1 row_mask:0xf bank_mask:0xf bound_ctrl:1
	v_add_f32_dpp v66, v66, v66 row_ror:1 row_mask:0xf bank_mask:0xf bound_ctrl:1
	s_waitcnt lgkmcnt(7)
	v_pk_fma_f32 v[6:7], v[22:23], v[2:3], v[6:7]
	v_add_f32_dpp v34, v34, v34 row_ror:2 row_mask:0xf bank_mask:0xf bound_ctrl:1
	v_add_f32_dpp v66, v66, v66 row_ror:2 row_mask:0xf bank_mask:0xf bound_ctrl:1
	v_pk_mul_f32 v[8:9], v[8:9], v[28:29] op_sel_hi:[1,0]
	v_add_f32_dpp v34, v34, v34 row_ror:4 row_mask:0xf bank_mask:0xf bound_ctrl:1
	v_pk_fma_f32 v[8:9], v[24:25], v[4:5], v[8:9]
	ds_write2st64_b32 v41, v36, v66 offset0:6 offset1:7
	v_add_f32_dpp v34, v34, v34 row_ror:8 row_mask:0xf bank_mask:0xf bound_ctrl:1
	v_pk_fma_f32 v[22:23], v[14:15], v[34:35], v[6:7] op_sel_hi:[1,0,1]
	v_pk_fma_f32 v[24:25], v[16:17], v[34:35], v[8:9] op_sel_hi:[1,0,1]
	s_waitcnt lgkmcnt(4)
	v_pk_mul_f32 v[34:35], v[22:23], v[50:51]
	v_pk_mul_f32 v[36:37], v[22:23], v[18:19]
	v_pk_fma_f32 v[34:35], v[24:25], v[52:53], v[34:35]
	v_pk_fma_f32 v[36:37], v[24:25], v[20:21], v[36:37]
	ds_read_b128 v[10:13], v38 offset:16192
	ds_read_b128 v[6:9], v38 offset:15936
	ds_read_b32 v28, v39 offset:16960
	ds_read_b128 v[2:5], v38 offset:15680
	ds_read_b128 v[14:17], v38 offset:16448
	ds_read_b128 v[18:21], v38 offset:16704
	v_add_f32_e32 v34, v34, v35
	v_add_f32_e32 v36, v36, v37
	v_pk_mul_f32 v[46:47], v[46:47], v[62:63] op_sel_hi:[1,0]
	v_add_f32_dpp v34, v34, v34 row_ror:1 row_mask:0xf bank_mask:0xf bound_ctrl:1
	v_add_f32_dpp v36, v36, v36 row_ror:1 row_mask:0xf bank_mask:0xf bound_ctrl:1
	s_waitcnt lgkmcnt(8)
	v_pk_fma_f32 v[46:47], v[22:23], v[42:43], v[46:47]
	v_add_f32_dpp v34, v34, v34 row_ror:2 row_mask:0xf bank_mask:0xf bound_ctrl:1
	v_add_f32_dpp v36, v36, v36 row_ror:2 row_mask:0xf bank_mask:0xf bound_ctrl:1
	v_pk_mul_f32 v[48:49], v[48:49], v[62:63] op_sel_hi:[1,0]
	v_add_f32_dpp v34, v34, v34 row_ror:4 row_mask:0xf bank_mask:0xf bound_ctrl:1
	v_pk_fma_f32 v[48:49], v[24:25], v[44:45], v[48:49]
	s_nop 0
	v_add_f32_dpp v34, v34, v34 row_ror:8 row_mask:0xf bank_mask:0xf bound_ctrl:1
	v_pk_fma_f32 v[22:23], v[54:55], v[34:35], v[46:47] op_sel_hi:[1,0,1]
	v_pk_fma_f32 v[24:25], v[56:57], v[34:35], v[48:49] op_sel_hi:[1,0,1]
	s_waitcnt lgkmcnt(3)
	v_pk_mul_f32 v[34:35], v[22:23], v[10:11]
	v_pk_mul_f32 v[66:67], v[22:23], v[58:59]
	v_pk_fma_f32 v[34:35], v[24:25], v[12:13], v[34:35]
	v_pk_fma_f32 v[66:67], v[24:25], v[60:61], v[66:67]
	ds_read_b128 v[50:53], v38 offset:17760
	ds_read_b128 v[46:49], v38 offset:17504
	ds_read_b32 v62, v39 offset:18528
	ds_read_b128 v[42:45], v38 offset:17248
	ds_read_b128 v[54:57], v38 offset:18016
	ds_read_b128 v[58:61], v38 offset:18272
	v_add_f32_e32 v34, v34, v35
	v_add_f32_e32 v66, v66, v67
	v_pk_mul_f32 v[6:7], v[6:7], v[28:29] op_sel_hi:[1,0]
	v_add_f32_dpp v34, v34, v34 row_ror:1 row_mask:0xf bank_mask:0xf bound_ctrl:1
	v_add_f32_dpp v66, v66, v66 row_ror:1 row_mask:0xf bank_mask:0xf bound_ctrl:1
	s_waitcnt lgkmcnt(7)
	v_pk_fma_f32 v[6:7], v[22:23], v[2:3], v[6:7]
	v_add_f32_dpp v34, v34, v34 row_ror:2 row_mask:0xf bank_mask:0xf bound_ctrl:1
	v_add_f32_dpp v66, v66, v66 row_ror:2 row_mask:0xf bank_mask:0xf bound_ctrl:1
	v_pk_mul_f32 v[8:9], v[8:9], v[28:29] op_sel_hi:[1,0]
	v_add_f32_dpp v34, v34, v34 row_ror:4 row_mask:0xf bank_mask:0xf bound_ctrl:1
	v_pk_fma_f32 v[8:9], v[24:25], v[4:5], v[8:9]
	ds_write2st64_b32 v41, v36, v66 offset0:8 offset1:9
	v_add_f32_dpp v34, v34, v34 row_ror:8 row_mask:0xf bank_mask:0xf bound_ctrl:1
	v_pk_fma_f32 v[22:23], v[14:15], v[34:35], v[6:7] op_sel_hi:[1,0,1]
	v_pk_fma_f32 v[24:25], v[16:17], v[34:35], v[8:9] op_sel_hi:[1,0,1]
	s_waitcnt lgkmcnt(4)
	v_pk_mul_f32 v[34:35], v[22:23], v[50:51]
	v_pk_mul_f32 v[36:37], v[22:23], v[18:19]
	v_pk_fma_f32 v[34:35], v[24:25], v[52:53], v[34:35]
	v_pk_fma_f32 v[36:37], v[24:25], v[20:21], v[36:37]
	ds_read_b128 v[10:13], v38 offset:19328
	ds_read_b128 v[6:9], v38 offset:19072
	ds_read_b32 v28, v39 offset:20096
	ds_read_b128 v[2:5], v38 offset:18816
	ds_read_b128 v[14:17], v38 offset:19584
	ds_read_b128 v[18:21], v38 offset:19840
	v_add_f32_e32 v34, v34, v35
	v_add_f32_e32 v36, v36, v37
	v_pk_mul_f32 v[46:47], v[46:47], v[62:63] op_sel_hi:[1,0]
	v_add_f32_dpp v34, v34, v34 row_ror:1 row_mask:0xf bank_mask:0xf bound_ctrl:1
	v_add_f32_dpp v36, v36, v36 row_ror:1 row_mask:0xf bank_mask:0xf bound_ctrl:1
	s_waitcnt lgkmcnt(8)
	v_pk_fma_f32 v[46:47], v[22:23], v[42:43], v[46:47]
	v_add_f32_dpp v34, v34, v34 row_ror:2 row_mask:0xf bank_mask:0xf bound_ctrl:1
	v_add_f32_dpp v36, v36, v36 row_ror:2 row_mask:0xf bank_mask:0xf bound_ctrl:1
	v_pk_mul_f32 v[48:49], v[48:49], v[62:63] op_sel_hi:[1,0]
	v_add_f32_dpp v34, v34, v34 row_ror:4 row_mask:0xf bank_mask:0xf bound_ctrl:1
	v_pk_fma_f32 v[48:49], v[24:25], v[44:45], v[48:49]
	s_nop 0
	v_add_f32_dpp v34, v34, v34 row_ror:8 row_mask:0xf bank_mask:0xf bound_ctrl:1
	v_pk_fma_f32 v[22:23], v[54:55], v[34:35], v[46:47] op_sel_hi:[1,0,1]
	v_pk_fma_f32 v[24:25], v[56:57], v[34:35], v[48:49] op_sel_hi:[1,0,1]
	s_waitcnt lgkmcnt(3)
; template <int CTRL> __device__ __forceinline__ float dpp_f(float x) { return __int_as_float(__builtin_amdgcn_update_dpp(0, __float_as_int(x), CTRL, 0xf, 0xf, false)); }
; __device__ __forceinline__ void p8_scan(const Args& a, LAS unsigned char* lds) {
;     ...
;                 for (int tt = 0; tt < TC; ++tt) {
;                     ScanOps n; scan_ld(n, bt + (tt + 1 < TC ? tt + 1 : tt) * SPITCH, jq4, myrow);
;                     __builtin_amdgcn_sched_barrier(0);
;                     f32x2 ta = S01 * o.al.lo, ty = S01 * o.wr.lo; ta = S23 * o.al.hi + ta; ty = S23 * o.wr.hi + ty;
;                     float pa = ta.x + ta.y, py = ty.x + ty.y;
;                     f32x2 kv01 = o.kv.lo * o.vi, kv23 = o.kv.hi * o.vi;
;     ...
;                     asm volatile("" : "+v"(kv01), "+v"(kv23), "+v"(vc));
;                     pa += dpp_f<0x121>(pa); py += dpp_f<0x121>(py); pa += dpp_f<0x122>(pa); py += dpp_f<0x122>(py);
;                     pa += dpp_f<0x124>(pa); pa += dpp_f<0x128>(pa);
;                     S01 = S01 * o.wv.lo + (o.be.lo * pa + kv01);
;                     S23 = S23 * o.wv.hi + (o.be.hi * pa + kv23);
;     ...
;                     __builtin_amdgcn_sched_barrier(0);
;                     o = n;
;                 }
	v_pk_mul_f32 v[34:35], v[22:23], v[10:11]
	v_pk_mul_f32 v[66:67], v[22:23], v[58:59]
	v_pk_fma_f32 v[34:35], v[24:25], v[12:13], v[34:35]
	v_pk_fma_f32 v[66:67], v[24:25], v[60:61], v[66:67]
	ds_read_b128 v[50:53], v38 offset:20896
	ds_read_b128 v[46:49], v38 offset:20640
	ds_read_b32 v62, v39 offset:21664
	ds_read_b128 v[42:45], v38 offset:20384
	ds_read_b128 v[54:57], v38 offset:21152
	ds_read_b128 v[58:61], v38 offset:21408
	v_add_f32_e32 v34, v34, v35
	v_add_f32_e32 v66, v66, v67
	v_pk_mul_f32 v[6:7], v[6:7], v[28:29] op_sel_hi:[1,0]
	v_add_f32_dpp v34, v34, v34 row_ror:1 row_mask:0xf bank_mask:0xf bound_ctrl:1
	v_add_f32_dpp v66, v66, v66 row_ror:1 row_mask:0xf bank_mask:0xf bound_ctrl:1
	s_waitcnt lgkmcnt(7)
	v_pk_fma_f32 v[6:7], v[22:23], v[2:3], v[6:7]
	v_add_f32_dpp v34, v34, v34 row_ror:2 row_mask:0xf bank_mask:0xf bound_ctrl:1
	v_add_f32_dpp v66, v66, v66 row_ror:2 row_mask:0xf bank_mask:0xf bound_ctrl:1
	v_pk_mul_f32 v[8:9], v[8:9], v[28:29] op_sel_hi:[1,0]
	v_add_f32_dpp v34, v34, v34 row_ror:4 row_mask:0xf bank_mask:0xf bound_ctrl:1
	v_pk_fma_f32 v[8:9], v[24:25], v[4:5], v[8:9]
	ds_write2st64_b32 v41, v36, v66 offset0:10 offset1:11
	v_add_f32_dpp v34, v34, v34 row_ror:8 row_mask:0xf bank_mask:0xf bound_ctrl:1
	v_pk_fma_f32 v[22:23], v[14:15], v[34:35], v[6:7] op_sel_hi:[1,0,1]
	v_pk_fma_f32 v[24:25], v[16:17], v[34:35], v[8:9] op_sel_hi:[1,0,1]
	s_waitcnt lgkmcnt(4)
	v_pk_mul_f32 v[34:35], v[22:23], v[50:51]
	v_pk_mul_f32 v[36:37], v[22:23], v[18:19]
	v_pk_fma_f32 v[34:35], v[24:25], v[52:53], v[34:35]
	v_pk_fma_f32 v[36:37], v[24:25], v[20:21], v[36:37]
	ds_read_b128 v[10:13], v38 offset:22464
	ds_read_b128 v[6:9], v38 offset:22208
	ds_read_b32 v28, v39 offset:23232
	ds_read_b128 v[2:5], v38 offset:21952
	ds_read_b128 v[14:17], v38 offset:22720
	ds_read_b128 v[18:21], v38 offset:22976
	v_add_f32_e32 v34, v34, v35
	v_add_f32_e32 v36, v36, v37
	v_pk_mul_f32 v[46:47], v[46:47], v[62:63] op_sel_hi:[1,0]
	v_add_f32_dpp v34, v34, v34 row_ror:1 row_mask:0xf bank_mask:0xf bound_ctrl:1
	v_add_f32_dpp v36, v36, v36 row_ror:1 row_mask:0xf bank_mask:0xf bound_ctrl:1
	s_waitcnt lgkmcnt(8)
	v_pk_fma_f32 v[46:47], v[22:23], v[42:43], v[46:47]
	v_add_f32_dpp v34, v34, v34 row_ror:2 row_mask:0xf bank_mask:0xf bound_ctrl:1
	v_add_f32_dpp v36, v36, v36 row_ror:2 row_mask:0xf bank_mask:0xf bound_ctrl:1
	v_pk_mul_f32 v[48:49], v[48:49], v[62:63] op_sel_hi:[1,0]
	v_add_f32_dpp v34, v34, v34 row_ror:4 row_mask:0xf bank_mask:0xf bound_ctrl:1
	v_pk_fma_f32 v[48:49], v[24:25], v[44:45], v[48:49]
	s_nop 0
	v_add_f32_dpp v34, v34, v34 row_ror:8 row_mask:0xf bank_mask:0xf bound_ctrl:1
	v_pk_fma_f32 v[22:23], v[54:55], v[34:35], v[46:47] op_sel_hi:[1,0,1]
	v_pk_fma_f32 v[24:25], v[56:57], v[34:35], v[48:49] op_sel_hi:[1,0,1]
	s_waitcnt lgkmcnt(3)
	v_pk_mul_f32 v[34:35], v[22:23], v[10:11]
	v_pk_mul_f32 v[66:67], v[22:23], v[58:59]
	v_pk_fma_f32 v[34:35], v[24:25], v[12:13], v[34:35]
	v_pk_fma_f32 v[66:67], v[24:25], v[60:61], v[66:67]
	ds_read_b128 v[50:53], v38 offset:24032
	ds_read_b128 v[46:49], v38 offset:23776
	ds_read_b32 v62, v39 offset:24800
	ds_read_b128 v[42:45], v38 offset:23520
	ds_read_b128 v[54:57], v38 offset:24288
	ds_read_b128 v[58:61], v38 offset:24544
	v_add_f32_e32 v34, v34, v35
	v_add_f32_e32 v66, v66, v67
	v_pk_mul_f32 v[6:7], v[6:7], v[28:29] op_sel_hi:[1,0]
	v_add_f32_dpp v34, v34, v34 row_ror:1 row_mask:0xf bank_mask:0xf bound_ctrl:1
	v_add_f32_dpp v66, v66, v66 row_ror:1 row_mask:0xf bank_mask:0xf bound_ctrl:1
	s_waitcnt lgkmcnt(7)
	v_pk_fma_f32 v[6:7], v[22:23], v[2:3], v[6:7]
	v_add_f32_dpp v34, v34, v34 row_ror:2 row_mask:0xf bank_mask:0xf bound_ctrl:1
	v_add_f32_dpp v66, v66, v66 row_ror:2 row_mask:0xf bank_mask:0xf bound_ctrl:1
	v_pk_mul_f32 v[8:9], v[8:9], v[28:29] op_sel_hi:[1,0]
	v_add_f32_dpp v34, v34, v34 row_ror:4 row_mask:0xf bank_mask:0xf bound_ctrl:1
	v_pk_fma_f32 v[8:9], v[24:25], v[4:5], v[8:9]
	ds_write2st64_b32 v41, v36, v66 offset0:12 offset1:13
	v_add_f32_dpp v34, v34, v34 row_ror:8 row_mask:0xf bank_mask:0xf bound_ctrl:1
	v_pk_fma_f32 v[22:23], v[14:15], v[34:35], v[6:7] op_sel_hi:[1,0,1]
	v_pk_fma_f32 v[24:25], v[16:17], v[34:35], v[8:9] op_sel_hi:[1,0,1]
	s_waitcnt lgkmcnt(4)
	v_pk_mul_f32 v[34:35], v[22:23], v[50:51]
	v_pk_mul_f32 v[36:37], v[22:23], v[18:19]
	v_pk_fma_f32 v[34:35], v[24:25], v[52:53], v[34:35]
	v_pk_fma_f32 v[36:37], v[24:25], v[20:21], v[36:37]
	ds_read_b128 v[10:13], v38 offset:25600
	ds_read_b128 v[6:9], v38 offset:25344
	ds_read_b32 v28, v39 offset:26368
	ds_read_b128 v[2:5], v38 offset:25088
	ds_read_b128 v[14:17], v38 offset:25856
	ds_read_b128 v[18:21], v38 offset:26112
	v_add_f32_e32 v34, v34, v35
	v_add_f32_e32 v36, v36, v37
	v_pk_mul_f32 v[46:47], v[46:47], v[62:63] op_sel_hi:[1,0]
	v_add_f32_dpp v34, v34, v34 row_ror:1 row_mask:0xf bank_mask:0xf bound_ctrl:1
	v_add_f32_dpp v36, v36, v36 row_ror:1 row_mask:0xf bank_mask:0xf bound_ctrl:1
	s_waitcnt lgkmcnt(8)
	v_pk_fma_f32 v[46:47], v[22:23], v[42:43], v[46:47]
	v_add_f32_dpp v34, v34, v34 row_ror:2 row_mask:0xf bank_mask:0xf bound_ctrl:1
	v_add_f32_dpp v36, v36, v36 row_ror:2 row_mask:0xf bank_mask:0xf bound_ctrl:1
	v_pk_mul_f32 v[48:49], v[48:49], v[62:63] op_sel_hi:[1,0]
	v_add_f32_dpp v34, v34, v34 row_ror:4 row_mask:0xf bank_mask:0xf bound_ctrl:1
	v_pk_fma_f32 v[48:49], v[24:25], v[44:45], v[48:49]
	s_nop 0
	v_add_f32_dpp v34, v34, v34 row_ror:8 row_mask:0xf bank_mask:0xf bound_ctrl:1
	v_pk_fma_f32 v[22:23], v[54:55], v[34:35], v[46:47] op_sel_hi:[1,0,1]
	v_pk_fma_f32 v[24:25], v[56:57], v[34:35], v[48:49] op_sel_hi:[1,0,1]
	s_waitcnt lgkmcnt(3)
; template <int CTRL> __device__ __forceinline__ float dpp_f(float x) { return __int_as_float(__builtin_amdgcn_update_dpp(0, __float_as_int(x), CTRL, 0xf, 0xf, false)); }
; __device__ __forceinline__ void p8_scan(const Args& a, LAS unsigned char* lds) {
;     ...
;                 for (int tt = 0; tt < TC; ++tt) {
;                     ScanOps n; scan_ld(n, bt + (tt + 1 < TC ? tt + 1 : tt) * SPITCH, jq4, myrow);
;                     __builtin_amdgcn_sched_barrier(0);
;                     f32x2 ta = S01 * o.al.lo, ty = S01 * o.wr.lo; ta = S23 * o.al.hi + ta; ty = S23 * o.wr.hi + ty;
;                     float pa = ta.x + ta.y, py = ty.x + ty.y;
;                     f32x2 kv01 = o.kv.lo * o.vi, kv23 = o.kv.hi * o.vi;
;     ...
;                     asm volatile("" : "+v"(kv01), "+v"(kv23), "+v"(vc));
;                     pa += dpp_f<0x121>(pa); py += dpp_f<0x121>(py); pa += dpp_f<0x122>(pa); py += dpp_f<0x122>(py);
;                     pa += dpp_f<0x124>(pa); pa += dpp_f<0x128>(pa);
;                     S01 = S01 * o.wv.lo + (o.be.lo * pa + kv01);
;                     S23 = S23 * o.wv.hi + (o.be.hi * pa + kv23);
;     ...
;                     __builtin_amdgcn_sched_barrier(0);
;                     o = n;
;                 }
	v_pk_mul_f32 v[34:35], v[22:23], v[10:11]
	v_pk_mul_f32 v[66:67], v[22:23], v[58:59]
	v_pk_fma_f32 v[34:35], v[24:25], v[12:13], v[34:35]
	v_pk_fma_f32 v[66:67], v[24:25], v[60:61], v[66:67]
	ds_read_b128 v[50:53], v38 offset:27168
	ds_read_b128 v[46:49], v38 offset:26912
	ds_read_b32 v62, v39 offset:27936
	ds_read_b128 v[42:45], v38 offset:26656
	ds_read_b128 v[54:57], v38 offset:27424
	ds_read_b128 v[58:61], v38 offset:27680
	v_add_f32_e32 v34, v34, v35
	v_add_f32_e32 v66, v66, v67
	v_pk_mul_f32 v[6:7], v[6:7], v[28:29] op_sel_hi:[1,0]
	v_add_f32_dpp v34, v34, v34 row_ror:1 row_mask:0xf bank_mask:0xf bound_ctrl:1
	v_add_f32_dpp v66, v66, v66 row_ror:1 row_mask:0xf bank_mask:0xf bound_ctrl:1
	s_waitcnt lgkmcnt(7)
	v_pk_fma_f32 v[6:7], v[22:23], v[2:3], v[6:7]
	v_add_f32_dpp v34, v34, v34 row_ror:2 row_mask:0xf bank_mask:0xf bound_ctrl:1
	v_add_f32_dpp v66, v66, v66 row_ror:2 row_mask:0xf bank_mask:0xf bound_ctrl:1
	v_pk_mul_f32 v[8:9], v[8:9], v[28:29] op_sel_hi:[1,0]
	v_add_f32_dpp v34, v34, v34 row_ror:4 row_mask:0xf bank_mask:0xf bound_ctrl:1
	v_pk_fma_f32 v[8:9], v[24:25], v[4:5], v[8:9]
	ds_write2st64_b32 v41, v36, v66 offset0:14 offset1:15
	v_add_f32_dpp v34, v34, v34 row_ror:8 row_mask:0xf bank_mask:0xf bound_ctrl:1
	v_pk_fma_f32 v[22:23], v[14:15], v[34:35], v[6:7] op_sel_hi:[1,0,1]
	v_pk_fma_f32 v[24:25], v[16:17], v[34:35], v[8:9] op_sel_hi:[1,0,1]
	s_waitcnt lgkmcnt(4)
	v_pk_mul_f32 v[34:35], v[22:23], v[50:51]
	v_pk_mul_f32 v[36:37], v[22:23], v[18:19]
	v_pk_fma_f32 v[34:35], v[24:25], v[52:53], v[34:35]
	v_pk_fma_f32 v[36:37], v[24:25], v[20:21], v[36:37]
	ds_read_b128 v[10:13], v38 offset:28736
	ds_read_b128 v[6:9], v38 offset:28480
	ds_read_b32 v28, v39 offset:29504
	ds_read_b128 v[2:5], v38 offset:28224
	ds_read_b128 v[14:17], v38 offset:28992
	ds_read_b128 v[18:21], v38 offset:29248
	v_add_f32_e32 v34, v34, v35
	v_add_f32_e32 v36, v36, v37
	v_pk_mul_f32 v[46:47], v[46:47], v[62:63] op_sel_hi:[1,0]
	v_add_f32_dpp v34, v34, v34 row_ror:1 row_mask:0xf bank_mask:0xf bound_ctrl:1
	v_add_f32_dpp v36, v36, v36 row_ror:1 row_mask:0xf bank_mask:0xf bound_ctrl:1
	s_waitcnt lgkmcnt(8)
	v_pk_fma_f32 v[46:47], v[22:23], v[42:43], v[46:47]
	v_add_f32_dpp v34, v34, v34 row_ror:2 row_mask:0xf bank_mask:0xf bound_ctrl:1
	v_add_f32_dpp v36, v36, v36 row_ror:2 row_mask:0xf bank_mask:0xf bound_ctrl:1
	v_pk_mul_f32 v[48:49], v[48:49], v[62:63] op_sel_hi:[1,0]
	v_add_f32_dpp v34, v34, v34 row_ror:4 row_mask:0xf bank_mask:0xf bound_ctrl:1
	v_pk_fma_f32 v[48:49], v[24:25], v[44:45], v[48:49]
	s_nop 0
	v_add_f32_dpp v34, v34, v34 row_ror:8 row_mask:0xf bank_mask:0xf bound_ctrl:1
	v_pk_fma_f32 v[22:23], v[54:55], v[34:35], v[46:47] op_sel_hi:[1,0,1]
	v_pk_fma_f32 v[24:25], v[56:57], v[34:35], v[48:49] op_sel_hi:[1,0,1]
	s_waitcnt lgkmcnt(3)
	v_pk_mul_f32 v[34:35], v[22:23], v[10:11]
	v_pk_mul_f32 v[66:67], v[22:23], v[58:59]
	v_pk_fma_f32 v[34:35], v[24:25], v[12:13], v[34:35]
	v_pk_fma_f32 v[66:67], v[24:25], v[60:61], v[66:67]
	ds_read_b128 v[50:53], v38 offset:30304
	ds_read_b128 v[46:49], v38 offset:30048
	ds_read_b32 v62, v39 offset:31072
	ds_read_b128 v[42:45], v38 offset:29792
	ds_read_b128 v[54:57], v38 offset:30560
	ds_read_b128 v[58:61], v38 offset:30816
	v_add_f32_e32 v34, v34, v35
	v_add_f32_e32 v66, v66, v67
	v_pk_mul_f32 v[6:7], v[6:7], v[28:29] op_sel_hi:[1,0]
	v_add_f32_dpp v34, v34, v34 row_ror:1 row_mask:0xf bank_mask:0xf bound_ctrl:1
	v_add_f32_dpp v66, v66, v66 row_ror:1 row_mask:0xf bank_mask:0xf bound_ctrl:1
	s_waitcnt lgkmcnt(7)
	v_pk_fma_f32 v[6:7], v[22:23], v[2:3], v[6:7]
	v_add_f32_dpp v34, v34, v34 row_ror:2 row_mask:0xf bank_mask:0xf bound_ctrl:1
	v_add_f32_dpp v66, v66, v66 row_ror:2 row_mask:0xf bank_mask:0xf bound_ctrl:1
	v_pk_mul_f32 v[8:9], v[8:9], v[28:29] op_sel_hi:[1,0]
	v_add_f32_dpp v34, v34, v34 row_ror:4 row_mask:0xf bank_mask:0xf bound_ctrl:1
	v_pk_fma_f32 v[8:9], v[24:25], v[4:5], v[8:9]
	ds_write2st64_b32 v41, v36, v66 offset0:16 offset1:17
	v_add_f32_dpp v34, v34, v34 row_ror:8 row_mask:0xf bank_mask:0xf bound_ctrl:1
	v_pk_fma_f32 v[22:23], v[14:15], v[34:35], v[6:7] op_sel_hi:[1,0,1]
	v_pk_fma_f32 v[24:25], v[16:17], v[34:35], v[8:9] op_sel_hi:[1,0,1]
	s_waitcnt lgkmcnt(4)
	v_pk_mul_f32 v[34:35], v[22:23], v[50:51]
	v_pk_mul_f32 v[36:37], v[22:23], v[18:19]
	v_pk_fma_f32 v[34:35], v[24:25], v[52:53], v[34:35]
	v_pk_fma_f32 v[36:37], v[24:25], v[20:21], v[36:37]
	ds_read_b128 v[10:13], v38 offset:31872
	ds_read_b128 v[6:9], v38 offset:31616
	ds_read_b32 v28, v39 offset:32640
	ds_read_b128 v[2:5], v38 offset:31360
	ds_read_b128 v[14:17], v38 offset:32128
	ds_read_b128 v[18:21], v38 offset:32384
	v_add_f32_e32 v34, v34, v35
	v_add_f32_e32 v36, v36, v37
	v_pk_mul_f32 v[46:47], v[46:47], v[62:63] op_sel_hi:[1,0]
	v_add_f32_dpp v34, v34, v34 row_ror:1 row_mask:0xf bank_mask:0xf bound_ctrl:1
	v_add_f32_dpp v36, v36, v36 row_ror:1 row_mask:0xf bank_mask:0xf bound_ctrl:1
	s_waitcnt lgkmcnt(8)
	v_pk_fma_f32 v[46:47], v[22:23], v[42:43], v[46:47]
	v_add_f32_dpp v34, v34, v34 row_ror:2 row_mask:0xf bank_mask:0xf bound_ctrl:1
	v_add_f32_dpp v36, v36, v36 row_ror:2 row_mask:0xf bank_mask:0xf bound_ctrl:1
	v_pk_mul_f32 v[48:49], v[48:49], v[62:63] op_sel_hi:[1,0]
	v_add_f32_dpp v34, v34, v34 row_ror:4 row_mask:0xf bank_mask:0xf bound_ctrl:1
	v_pk_fma_f32 v[48:49], v[24:25], v[44:45], v[48:49]
	s_nop 0
	v_add_f32_dpp v34, v34, v34 row_ror:8 row_mask:0xf bank_mask:0xf bound_ctrl:1
	v_pk_fma_f32 v[22:23], v[54:55], v[34:35], v[46:47] op_sel_hi:[1,0,1]
	v_pk_fma_f32 v[24:25], v[56:57], v[34:35], v[48:49] op_sel_hi:[1,0,1]
	s_waitcnt lgkmcnt(3)
; template <int CTRL> __device__ __forceinline__ float dpp_f(float x) { return __int_as_float(__builtin_amdgcn_update_dpp(0, __float_as_int(x), CTRL, 0xf, 0xf, false)); }
; __device__ __forceinline__ void p8_scan(const Args& a, LAS unsigned char* lds) {
;     ...
;                 for (int tt = 0; tt < TC; ++tt) {
;                     ScanOps n; scan_ld(n, bt + (tt + 1 < TC ? tt + 1 : tt) * SPITCH, jq4, myrow);
;                     __builtin_amdgcn_sched_barrier(0);
;                     f32x2 ta = S01 * o.al.lo, ty = S01 * o.wr.lo; ta = S23 * o.al.hi + ta; ty = S23 * o.wr.hi + ty;
;                     float pa = ta.x + ta.y, py = ty.x + ty.y;
;                     f32x2 kv01 = o.kv.lo * o.vi, kv23 = o.kv.hi * o.vi;
;     ...
;                     asm volatile("" : "+v"(kv01), "+v"(kv23), "+v"(vc));
;                     pa += dpp_f<0x121>(pa); py += dpp_f<0x121>(py); pa += dpp_f<0x122>(pa); py += dpp_f<0x122>(py);
;                     pa += dpp_f<0x124>(pa); pa += dpp_f<0x128>(pa);
;                     S01 = S01 * o.wv.lo + (o.be.lo * pa + kv01);
;                     S23 = S23 * o.wv.hi + (o.be.hi * pa + kv23);
;     ...
;                     __builtin_amdgcn_sched_barrier(0);
;                     o = n;
;                 }
	v_pk_mul_f32 v[34:35], v[22:23], v[10:11]
	v_pk_mul_f32 v[66:67], v[22:23], v[58:59]
	v_pk_fma_f32 v[34:35], v[24:25], v[12:13], v[34:35]
	v_pk_fma_f32 v[66:67], v[24:25], v[60:61], v[66:67]
	ds_read_b128 v[50:53], v38 offset:33440
	ds_read_b128 v[46:49], v38 offset:33184
	ds_read_b32 v62, v39 offset:34208
	ds_read_b128 v[42:45], v38 offset:32928
	ds_read_b128 v[54:57], v38 offset:33696
	ds_read_b128 v[58:61], v38 offset:33952
	v_add_f32_e32 v34, v34, v35
	v_add_f32_e32 v66, v66, v67
	v_pk_mul_f32 v[6:7], v[6:7], v[28:29] op_sel_hi:[1,0]
	v_add_f32_dpp v34, v34, v34 row_ror:1 row_mask:0xf bank_mask:0xf bound_ctrl:1
	v_add_f32_dpp v66, v66, v66 row_ror:1 row_mask:0xf bank_mask:0xf bound_ctrl:1
	s_waitcnt lgkmcnt(7)
	v_pk_fma_f32 v[6:7], v[22:23], v[2:3], v[6:7]
	v_add_f32_dpp v34, v34, v34 row_ror:2 row_mask:0xf bank_mask:0xf bound_ctrl:1
	v_add_f32_dpp v66, v66, v66 row_ror:2 row_mask:0xf bank_mask:0xf bound_ctrl:1
	v_pk_mul_f32 v[8:9], v[8:9], v[28:29] op_sel_hi:[1,0]
	v_add_f32_dpp v34, v34, v34 row_ror:4 row_mask:0xf bank_mask:0xf bound_ctrl:1
	v_pk_fma_f32 v[8:9], v[24:25], v[4:5], v[8:9]
	ds_write2st64_b32 v41, v36, v66 offset0:18 offset1:19
	v_add_f32_dpp v34, v34, v34 row_ror:8 row_mask:0xf bank_mask:0xf bound_ctrl:1
	v_pk_fma_f32 v[22:23], v[14:15], v[34:35], v[6:7] op_sel_hi:[1,0,1]
	v_pk_fma_f32 v[24:25], v[16:17], v[34:35], v[8:9] op_sel_hi:[1,0,1]
	s_waitcnt lgkmcnt(4)
	v_pk_mul_f32 v[34:35], v[22:23], v[50:51]
	v_pk_mul_f32 v[36:37], v[22:23], v[18:19]
	v_pk_fma_f32 v[34:35], v[24:25], v[52:53], v[34:35]
	v_pk_fma_f32 v[36:37], v[24:25], v[20:21], v[36:37]
	ds_read_b128 v[10:13], v38 offset:35008
	ds_read_b128 v[6:9], v38 offset:34752
	ds_read_b32 v28, v39 offset:35776
	ds_read_b128 v[2:5], v38 offset:34496
	ds_read_b128 v[14:17], v38 offset:35264
	ds_read_b128 v[18:21], v38 offset:35520
	v_add_f32_e32 v34, v34, v35
	v_add_f32_e32 v36, v36, v37
	v_pk_mul_f32 v[46:47], v[46:47], v[62:63] op_sel_hi:[1,0]
	v_add_f32_dpp v34, v34, v34 row_ror:1 row_mask:0xf bank_mask:0xf bound_ctrl:1
	v_add_f32_dpp v36, v36, v36 row_ror:1 row_mask:0xf bank_mask:0xf bound_ctrl:1
	s_waitcnt lgkmcnt(8)
	v_pk_fma_f32 v[46:47], v[22:23], v[42:43], v[46:47]
	v_add_f32_dpp v34, v34, v34 row_ror:2 row_mask:0xf bank_mask:0xf bound_ctrl:1
	v_add_f32_dpp v36, v36, v36 row_ror:2 row_mask:0xf bank_mask:0xf bound_ctrl:1
	v_pk_mul_f32 v[48:49], v[48:49], v[62:63] op_sel_hi:[1,0]
	v_add_f32_dpp v34, v34, v34 row_ror:4 row_mask:0xf bank_mask:0xf bound_ctrl:1
	v_pk_fma_f32 v[48:49], v[24:25], v[44:45], v[48:49]
	s_nop 0
	v_add_f32_dpp v34, v34, v34 row_ror:8 row_mask:0xf bank_mask:0xf bound_ctrl:1
	v_pk_fma_f32 v[22:23], v[54:55], v[34:35], v[46:47] op_sel_hi:[1,0,1]
	v_pk_fma_f32 v[24:25], v[56:57], v[34:35], v[48:49] op_sel_hi:[1,0,1]
	s_waitcnt lgkmcnt(3)
	v_pk_mul_f32 v[34:35], v[22:23], v[10:11]
	v_pk_mul_f32 v[66:67], v[22:23], v[58:59]
	v_pk_fma_f32 v[34:35], v[24:25], v[12:13], v[34:35]
	v_pk_fma_f32 v[66:67], v[24:25], v[60:61], v[66:67]
	ds_read_b128 v[50:53], v38 offset:36576
	ds_read_b128 v[46:49], v38 offset:36320
	ds_read_b32 v62, v39 offset:37344
	ds_read_b128 v[42:45], v38 offset:36064
	ds_read_b128 v[54:57], v38 offset:36832
	ds_read_b128 v[58:61], v38 offset:37088
	v_add_f32_e32 v34, v34, v35
	v_add_f32_e32 v66, v66, v67
	v_pk_mul_f32 v[6:7], v[6:7], v[28:29] op_sel_hi:[1,0]
	v_add_f32_dpp v34, v34, v34 row_ror:1 row_mask:0xf bank_mask:0xf bound_ctrl:1
	v_add_f32_dpp v66, v66, v66 row_ror:1 row_mask:0xf bank_mask:0xf bound_ctrl:1
	s_waitcnt lgkmcnt(7)
	v_pk_fma_f32 v[6:7], v[22:23], v[2:3], v[6:7]
	v_add_f32_dpp v34, v34, v34 row_ror:2 row_mask:0xf bank_mask:0xf bound_ctrl:1
	v_add_f32_dpp v66, v66, v66 row_ror:2 row_mask:0xf bank_mask:0xf bound_ctrl:1
	v_pk_mul_f32 v[8:9], v[8:9], v[28:29] op_sel_hi:[1,0]
	v_add_f32_dpp v34, v34, v34 row_ror:4 row_mask:0xf bank_mask:0xf bound_ctrl:1
	v_pk_fma_f32 v[8:9], v[24:25], v[4:5], v[8:9]
	ds_write2st64_b32 v41, v36, v66 offset0:20 offset1:21
	v_add_f32_dpp v34, v34, v34 row_ror:8 row_mask:0xf bank_mask:0xf bound_ctrl:1
	v_pk_fma_f32 v[22:23], v[14:15], v[34:35], v[6:7] op_sel_hi:[1,0,1]
	v_pk_fma_f32 v[24:25], v[16:17], v[34:35], v[8:9] op_sel_hi:[1,0,1]
	s_waitcnt lgkmcnt(4)
	v_pk_mul_f32 v[34:35], v[22:23], v[50:51]
	v_pk_mul_f32 v[36:37], v[22:23], v[18:19]
	v_pk_fma_f32 v[34:35], v[24:25], v[52:53], v[34:35]
	v_pk_fma_f32 v[36:37], v[24:25], v[20:21], v[36:37]
	ds_read_b128 v[10:13], v38 offset:38144
	ds_read_b128 v[6:9], v38 offset:37888
	ds_read_b32 v28, v39 offset:38912
	ds_read_b128 v[2:5], v38 offset:37632
	ds_read_b128 v[14:17], v38 offset:38400
	ds_read_b128 v[18:21], v38 offset:38656
	v_add_f32_e32 v34, v34, v35
	v_add_f32_e32 v36, v36, v37
	v_pk_mul_f32 v[46:47], v[46:47], v[62:63] op_sel_hi:[1,0]
	v_add_f32_dpp v34, v34, v34 row_ror:1 row_mask:0xf bank_mask:0xf bound_ctrl:1
	v_add_f32_dpp v36, v36, v36 row_ror:1 row_mask:0xf bank_mask:0xf bound_ctrl:1
	s_waitcnt lgkmcnt(8)
	v_pk_fma_f32 v[46:47], v[22:23], v[42:43], v[46:47]
	v_add_f32_dpp v34, v34, v34 row_ror:2 row_mask:0xf bank_mask:0xf bound_ctrl:1
	v_add_f32_dpp v36, v36, v36 row_ror:2 row_mask:0xf bank_mask:0xf bound_ctrl:1
	v_pk_mul_f32 v[48:49], v[48:49], v[62:63] op_sel_hi:[1,0]
	v_add_f32_dpp v34, v34, v34 row_ror:4 row_mask:0xf bank_mask:0xf bound_ctrl:1
	v_pk_fma_f32 v[48:49], v[24:25], v[44:45], v[48:49]
	s_nop 0
	v_add_f32_dpp v34, v34, v34 row_ror:8 row_mask:0xf bank_mask:0xf bound_ctrl:1
	v_pk_fma_f32 v[22:23], v[54:55], v[34:35], v[46:47] op_sel_hi:[1,0,1]
	v_pk_fma_f32 v[24:25], v[56:57], v[34:35], v[48:49] op_sel_hi:[1,0,1]
	s_waitcnt lgkmcnt(3)
; template <int CTRL> __device__ __forceinline__ float dpp_f(float x) { return __int_as_float(__builtin_amdgcn_update_dpp(0, __float_as_int(x), CTRL, 0xf, 0xf, false)); }
; __device__ __forceinline__ void p8_scan(const Args& a, LAS unsigned char* lds) {
;     ...
;                 for (int tt = 0; tt < TC; ++tt) {
;                     ScanOps n; scan_ld(n, bt + (tt + 1 < TC ? tt + 1 : tt) * SPITCH, jq4, myrow);
;                     __builtin_amdgcn_sched_barrier(0);
;                     f32x2 ta = S01 * o.al.lo, ty = S01 * o.wr.lo; ta = S23 * o.al.hi + ta; ty = S23 * o.wr.hi + ty;
;                     float pa = ta.x + ta.y, py = ty.x + ty.y;
;                     f32x2 kv01 = o.kv.lo * o.vi, kv23 = o.kv.hi * o.vi;
;     ...
;                     asm volatile("" : "+v"(kv01), "+v"(kv23), "+v"(vc));
;                     pa += dpp_f<0x121>(pa); py += dpp_f<0x121>(py); pa += dpp_f<0x122>(pa); py += dpp_f<0x122>(py);
;                     pa += dpp_f<0x124>(pa); pa += dpp_f<0x128>(pa);
;                     S01 = S01 * o.wv.lo + (o.be.lo * pa + kv01);
;                     S23 = S23 * o.wv.hi + (o.be.hi * pa + kv23);
;     ...
;                     __builtin_amdgcn_sched_barrier(0);
;                     o = n;
;                 }
	v_pk_mul_f32 v[34:35], v[22:23], v[10:11]
	v_pk_mul_f32 v[66:67], v[22:23], v[58:59]
	v_pk_fma_f32 v[34:35], v[24:25], v[12:13], v[34:35]
	v_pk_fma_f32 v[66:67], v[24:25], v[60:61], v[66:67]
	ds_read_b128 v[50:53], v38 offset:39712
	ds_read_b128 v[46:49], v38 offset:39456
	ds_read_b32 v62, v39 offset:40480
	ds_read_b128 v[42:45], v38 offset:39200
	ds_read_b128 v[54:57], v38 offset:39968
	ds_read_b128 v[58:61], v38 offset:40224
	v_add_f32_e32 v34, v34, v35
	v_add_f32_e32 v66, v66, v67
	v_pk_mul_f32 v[6:7], v[6:7], v[28:29] op_sel_hi:[1,0]
	v_add_f32_dpp v34, v34, v34 row_ror:1 row_mask:0xf bank_mask:0xf bound_ctrl:1
	v_add_f32_dpp v66, v66, v66 row_ror:1 row_mask:0xf bank_mask:0xf bound_ctrl:1
	s_waitcnt lgkmcnt(7)
	v_pk_fma_f32 v[6:7], v[22:23], v[2:3], v[6:7]
	v_add_f32_dpp v34, v34, v34 row_ror:2 row_mask:0xf bank_mask:0xf bound_ctrl:1
	v_add_f32_dpp v66, v66, v66 row_ror:2 row_mask:0xf bank_mask:0xf bound_ctrl:1
	v_pk_mul_f32 v[8:9], v[8:9], v[28:29] op_sel_hi:[1,0]
	v_add_f32_dpp v34, v34, v34 row_ror:4 row_mask:0xf bank_mask:0xf bound_ctrl:1
	v_pk_fma_f32 v[8:9], v[24:25], v[4:5], v[8:9]
	ds_write2st64_b32 v41, v36, v66 offset0:22 offset1:23
	v_add_f32_dpp v34, v34, v34 row_ror:8 row_mask:0xf bank_mask:0xf bound_ctrl:1
	v_pk_fma_f32 v[22:23], v[14:15], v[34:35], v[6:7] op_sel_hi:[1,0,1]
	v_pk_fma_f32 v[24:25], v[16:17], v[34:35], v[8:9] op_sel_hi:[1,0,1]
	s_waitcnt lgkmcnt(4)
	v_pk_mul_f32 v[34:35], v[22:23], v[50:51]
	v_pk_mul_f32 v[36:37], v[22:23], v[18:19]
	v_pk_fma_f32 v[34:35], v[24:25], v[52:53], v[34:35]
	v_pk_fma_f32 v[36:37], v[24:25], v[20:21], v[36:37]
	ds_read_b128 v[10:13], v38 offset:41280
	ds_read_b128 v[6:9], v38 offset:41024
	ds_read_b32 v28, v39 offset:42048
	ds_read_b128 v[2:5], v38 offset:40768
	ds_read_b128 v[14:17], v38 offset:41536
	ds_read_b128 v[18:21], v38 offset:41792
	v_add_f32_e32 v34, v34, v35
	v_add_f32_e32 v36, v36, v37
	v_pk_mul_f32 v[46:47], v[46:47], v[62:63] op_sel_hi:[1,0]
	v_add_f32_dpp v34, v34, v34 row_ror:1 row_mask:0xf bank_mask:0xf bound_ctrl:1
	v_add_f32_dpp v36, v36, v36 row_ror:1 row_mask:0xf bank_mask:0xf bound_ctrl:1
	s_waitcnt lgkmcnt(8)
	v_pk_fma_f32 v[46:47], v[22:23], v[42:43], v[46:47]
	v_add_f32_dpp v34, v34, v34 row_ror:2 row_mask:0xf bank_mask:0xf bound_ctrl:1
	v_add_f32_dpp v36, v36, v36 row_ror:2 row_mask:0xf bank_mask:0xf bound_ctrl:1
	v_pk_mul_f32 v[48:49], v[48:49], v[62:63] op_sel_hi:[1,0]
	v_add_f32_dpp v34, v34, v34 row_ror:4 row_mask:0xf bank_mask:0xf bound_ctrl:1
	v_pk_fma_f32 v[48:49], v[24:25], v[44:45], v[48:49]
	s_nop 0
	v_add_f32_dpp v34, v34, v34 row_ror:8 row_mask:0xf bank_mask:0xf bound_ctrl:1
	v_pk_fma_f32 v[22:23], v[54:55], v[34:35], v[46:47] op_sel_hi:[1,0,1]
	v_pk_fma_f32 v[24:25], v[56:57], v[34:35], v[48:49] op_sel_hi:[1,0,1]
	s_waitcnt lgkmcnt(3)
	v_pk_mul_f32 v[34:35], v[22:23], v[10:11]
	v_pk_mul_f32 v[66:67], v[22:23], v[58:59]
	v_pk_fma_f32 v[34:35], v[24:25], v[12:13], v[34:35]
	v_pk_fma_f32 v[66:67], v[24:25], v[60:61], v[66:67]
	ds_read_b128 v[50:53], v38 offset:42848
	ds_read_b128 v[46:49], v38 offset:42592
	ds_read_b32 v62, v39 offset:43616
	ds_read_b128 v[42:45], v38 offset:42336
	ds_read_b128 v[54:57], v38 offset:43104
	ds_read_b128 v[58:61], v38 offset:43360
	v_add_f32_e32 v34, v34, v35
	v_add_f32_e32 v66, v66, v67
	v_pk_mul_f32 v[6:7], v[6:7], v[28:29] op_sel_hi:[1,0]
	v_add_f32_dpp v34, v34, v34 row_ror:1 row_mask:0xf bank_mask:0xf bound_ctrl:1
	v_add_f32_dpp v66, v66, v66 row_ror:1 row_mask:0xf bank_mask:0xf bound_ctrl:1
	s_waitcnt lgkmcnt(7)
	v_pk_fma_f32 v[6:7], v[22:23], v[2:3], v[6:7]
	v_add_f32_dpp v34, v34, v34 row_ror:2 row_mask:0xf bank_mask:0xf bound_ctrl:1
	v_add_f32_dpp v66, v66, v66 row_ror:2 row_mask:0xf bank_mask:0xf bound_ctrl:1
	v_pk_mul_f32 v[8:9], v[8:9], v[28:29] op_sel_hi:[1,0]
	v_add_f32_dpp v34, v34, v34 row_ror:4 row_mask:0xf bank_mask:0xf bound_ctrl:1
	v_pk_fma_f32 v[8:9], v[24:25], v[4:5], v[8:9]
	ds_write2st64_b32 v41, v36, v66 offset0:24 offset1:25
	v_add_f32_dpp v34, v34, v34 row_ror:8 row_mask:0xf bank_mask:0xf bound_ctrl:1
	v_pk_fma_f32 v[22:23], v[14:15], v[34:35], v[6:7] op_sel_hi:[1,0,1]
	v_pk_fma_f32 v[24:25], v[16:17], v[34:35], v[8:9] op_sel_hi:[1,0,1]
	s_waitcnt lgkmcnt(4)
	v_pk_mul_f32 v[34:35], v[22:23], v[50:51]
	v_pk_mul_f32 v[36:37], v[22:23], v[18:19]
	v_pk_fma_f32 v[34:35], v[24:25], v[52:53], v[34:35]
	v_pk_fma_f32 v[36:37], v[24:25], v[20:21], v[36:37]
	ds_read_b128 v[10:13], v38 offset:44416
	ds_read_b128 v[6:9], v38 offset:44160
	ds_read_b32 v28, v39 offset:45184
	ds_read_b128 v[2:5], v38 offset:43904
	ds_read_b128 v[14:17], v38 offset:44672
	ds_read_b128 v[18:21], v38 offset:44928
	v_add_f32_e32 v34, v34, v35
	v_add_f32_e32 v36, v36, v37
	v_pk_mul_f32 v[46:47], v[46:47], v[62:63] op_sel_hi:[1,0]
	v_add_f32_dpp v34, v34, v34 row_ror:1 row_mask:0xf bank_mask:0xf bound_ctrl:1
	v_add_f32_dpp v36, v36, v36 row_ror:1 row_mask:0xf bank_mask:0xf bound_ctrl:1
	s_waitcnt lgkmcnt(8)
	v_pk_fma_f32 v[46:47], v[22:23], v[42:43], v[46:47]
	v_add_f32_dpp v34, v34, v34 row_ror:2 row_mask:0xf bank_mask:0xf bound_ctrl:1
	v_add_f32_dpp v36, v36, v36 row_ror:2 row_mask:0xf bank_mask:0xf bound_ctrl:1
	v_pk_mul_f32 v[48:49], v[48:49], v[62:63] op_sel_hi:[1,0]
	v_add_f32_dpp v34, v34, v34 row_ror:4 row_mask:0xf bank_mask:0xf bound_ctrl:1
	v_pk_fma_f32 v[48:49], v[24:25], v[44:45], v[48:49]
	s_nop 0
	v_add_f32_dpp v34, v34, v34 row_ror:8 row_mask:0xf bank_mask:0xf bound_ctrl:1
	v_pk_fma_f32 v[22:23], v[54:55], v[34:35], v[46:47] op_sel_hi:[1,0,1]
	v_pk_fma_f32 v[24:25], v[56:57], v[34:35], v[48:49] op_sel_hi:[1,0,1]
	s_waitcnt lgkmcnt(3)
; template <int CTRL> __device__ __forceinline__ float dpp_f(float x) { return __int_as_float(__builtin_amdgcn_update_dpp(0, __float_as_int(x), CTRL, 0xf, 0xf, false)); }
; __device__ __forceinline__ void p8_scan(const Args& a, LAS unsigned char* lds) {
;     ...
;                 for (int tt = 0; tt < TC; ++tt) {
;                     ScanOps n; scan_ld(n, bt + (tt + 1 < TC ? tt + 1 : tt) * SPITCH, jq4, myrow);
;                     __builtin_amdgcn_sched_barrier(0);
;                     f32x2 ta = S01 * o.al.lo, ty = S01 * o.wr.lo; ta = S23 * o.al.hi + ta; ty = S23 * o.wr.hi + ty;
;                     float pa = ta.x + ta.y, py = ty.x + ty.y;
;                     f32x2 kv01 = o.kv.lo * o.vi, kv23 = o.kv.hi * o.vi;
;     ...
;                     asm volatile("" : "+v"(kv01), "+v"(kv23), "+v"(vc));
;                     pa += dpp_f<0x121>(pa); py += dpp_f<0x121>(py); pa += dpp_f<0x122>(pa); py += dpp_f<0x122>(py);
;                     pa += dpp_f<0x124>(pa); pa += dpp_f<0x128>(pa);
;                     S01 = S01 * o.wv.lo + (o.be.lo * pa + kv01);
;                     S23 = S23 * o.wv.hi + (o.be.hi * pa + kv23);
;     ...
;                     __builtin_amdgcn_sched_barrier(0);
;                     o = n;
;                 }
;                 __syncthreads();
	v_pk_mul_f32 v[34:35], v[22:23], v[10:11]
	v_pk_mul_f32 v[66:67], v[22:23], v[58:59]
	v_pk_fma_f32 v[34:35], v[24:25], v[12:13], v[34:35]
	v_pk_fma_f32 v[66:67], v[24:25], v[60:61], v[66:67]
	ds_read_b128 v[50:53], v38 offset:45984
	ds_read_b128 v[46:49], v38 offset:45728
	ds_read_b32 v62, v39 offset:46752
	ds_read_b128 v[42:45], v38 offset:45472
	ds_read_b128 v[54:57], v38 offset:46240
	ds_read_b128 v[58:61], v38 offset:46496
	v_add_f32_e32 v34, v34, v35
	v_add_f32_e32 v66, v66, v67
	v_pk_mul_f32 v[6:7], v[6:7], v[28:29] op_sel_hi:[1,0]
	v_add_f32_dpp v34, v34, v34 row_ror:1 row_mask:0xf bank_mask:0xf bound_ctrl:1
	v_add_f32_dpp v66, v66, v66 row_ror:1 row_mask:0xf bank_mask:0xf bound_ctrl:1
	s_waitcnt lgkmcnt(7)
	v_pk_fma_f32 v[6:7], v[22:23], v[2:3], v[6:7]
	v_add_f32_dpp v34, v34, v34 row_ror:2 row_mask:0xf bank_mask:0xf bound_ctrl:1
	v_add_f32_dpp v66, v66, v66 row_ror:2 row_mask:0xf bank_mask:0xf bound_ctrl:1
	v_pk_mul_f32 v[8:9], v[8:9], v[28:29] op_sel_hi:[1,0]
	v_add_f32_dpp v34, v34, v34 row_ror:4 row_mask:0xf bank_mask:0xf bound_ctrl:1
	v_pk_fma_f32 v[8:9], v[24:25], v[4:5], v[8:9]
	ds_write2st64_b32 v41, v36, v66 offset0:26 offset1:27
	v_add_f32_dpp v34, v34, v34 row_ror:8 row_mask:0xf bank_mask:0xf bound_ctrl:1
	v_pk_fma_f32 v[22:23], v[14:15], v[34:35], v[6:7] op_sel_hi:[1,0,1]
	v_pk_fma_f32 v[24:25], v[16:17], v[34:35], v[8:9] op_sel_hi:[1,0,1]
	s_waitcnt lgkmcnt(4)
	v_pk_mul_f32 v[34:35], v[22:23], v[50:51]
	v_pk_mul_f32 v[36:37], v[22:23], v[18:19]
	v_pk_fma_f32 v[34:35], v[24:25], v[52:53], v[34:35]
	v_pk_fma_f32 v[36:37], v[24:25], v[20:21], v[36:37]
	ds_read_b128 v[10:13], v38 offset:47552
	ds_read_b128 v[6:9], v38 offset:47296
	ds_read_b32 v28, v39 offset:48320
	ds_read_b128 v[2:5], v38 offset:47040
	ds_read_b128 v[14:17], v38 offset:47808
	ds_read_b128 v[18:21], v38 offset:48064
	v_add_f32_e32 v34, v34, v35
	v_add_f32_e32 v36, v36, v37
	v_pk_mul_f32 v[46:47], v[46:47], v[62:63] op_sel_hi:[1,0]
	v_add_f32_dpp v34, v34, v34 row_ror:1 row_mask:0xf bank_mask:0xf bound_ctrl:1
	v_add_f32_dpp v36, v36, v36 row_ror:1 row_mask:0xf bank_mask:0xf bound_ctrl:1
	s_waitcnt lgkmcnt(8)
	v_pk_fma_f32 v[46:47], v[22:23], v[42:43], v[46:47]
	v_add_f32_dpp v34, v34, v34 row_ror:2 row_mask:0xf bank_mask:0xf bound_ctrl:1
	v_add_f32_dpp v36, v36, v36 row_ror:2 row_mask:0xf bank_mask:0xf bound_ctrl:1
	v_pk_mul_f32 v[48:49], v[48:49], v[62:63] op_sel_hi:[1,0]
	v_add_f32_dpp v34, v34, v34 row_ror:4 row_mask:0xf bank_mask:0xf bound_ctrl:1
	v_pk_fma_f32 v[48:49], v[24:25], v[44:45], v[48:49]
	s_nop 0
	v_add_f32_dpp v34, v34, v34 row_ror:8 row_mask:0xf bank_mask:0xf bound_ctrl:1
	v_pk_fma_f32 v[22:23], v[54:55], v[34:35], v[46:47] op_sel_hi:[1,0,1]
	v_pk_fma_f32 v[24:25], v[56:57], v[34:35], v[48:49] op_sel_hi:[1,0,1]
	s_waitcnt lgkmcnt(3)
	v_pk_mul_f32 v[34:35], v[22:23], v[10:11]
	v_pk_mul_f32 v[66:67], v[22:23], v[58:59]
	v_pk_fma_f32 v[34:35], v[24:25], v[12:13], v[34:35]
	v_pk_fma_f32 v[66:67], v[24:25], v[60:61], v[66:67]
	ds_read_b128 v[50:53], v38 offset:49120
	ds_read_b128 v[46:49], v38 offset:48864
	ds_read_b32 v62, v39 offset:49888
	ds_read_b128 v[42:45], v38 offset:48608
	ds_read_b128 v[54:57], v38 offset:49376
	ds_read_b128 v[58:61], v38 offset:49632
	v_add_f32_e32 v34, v34, v35
	v_add_f32_e32 v66, v66, v67
	v_pk_mul_f32 v[6:7], v[6:7], v[28:29] op_sel_hi:[1,0]
	v_add_f32_dpp v34, v34, v34 row_ror:1 row_mask:0xf bank_mask:0xf bound_ctrl:1
	v_add_f32_dpp v66, v66, v66 row_ror:1 row_mask:0xf bank_mask:0xf bound_ctrl:1
	s_waitcnt lgkmcnt(7)
	v_pk_fma_f32 v[6:7], v[22:23], v[2:3], v[6:7]
	v_add_f32_dpp v34, v34, v34 row_ror:2 row_mask:0xf bank_mask:0xf bound_ctrl:1
	v_add_f32_dpp v66, v66, v66 row_ror:2 row_mask:0xf bank_mask:0xf bound_ctrl:1
	v_pk_mul_f32 v[8:9], v[8:9], v[28:29] op_sel_hi:[1,0]
	v_add_f32_dpp v34, v34, v34 row_ror:4 row_mask:0xf bank_mask:0xf bound_ctrl:1
	v_pk_fma_f32 v[8:9], v[24:25], v[4:5], v[8:9]
	ds_write2st64_b32 v41, v36, v66 offset0:28 offset1:29
	v_add_f32_dpp v34, v34, v34 row_ror:8 row_mask:0xf bank_mask:0xf bound_ctrl:1
	v_pk_fma_f32 v[22:23], v[14:15], v[34:35], v[6:7] op_sel_hi:[1,0,1]
	v_pk_fma_f32 v[24:25], v[16:17], v[34:35], v[8:9] op_sel_hi:[1,0,1]
	s_waitcnt lgkmcnt(4)
	v_pk_mul_f32 v[34:35], v[22:23], v[50:51]
	v_pk_mul_f32 v[36:37], v[22:23], v[18:19]
	v_pk_fma_f32 v[34:35], v[24:25], v[52:53], v[34:35]
	v_pk_fma_f32 v[36:37], v[24:25], v[20:21], v[36:37]
	v_add_f32_e32 v34, v34, v35
	v_add_f32_e32 v36, v36, v37
	v_pk_mul_f32 v[46:47], v[46:47], v[62:63] op_sel_hi:[1,0]
	v_add_f32_dpp v34, v34, v34 row_ror:1 row_mask:0xf bank_mask:0xf bound_ctrl:1
	v_add_f32_dpp v36, v36, v36 row_ror:1 row_mask:0xf bank_mask:0xf bound_ctrl:1
	s_waitcnt lgkmcnt(1)
	v_pk_fma_f32 v[46:47], v[22:23], v[42:43], v[46:47]
	v_add_f32_dpp v34, v34, v34 row_ror:2 row_mask:0xf bank_mask:0xf bound_ctrl:1
	v_add_f32_dpp v36, v36, v36 row_ror:2 row_mask:0xf bank_mask:0xf bound_ctrl:1
	v_pk_mul_f32 v[48:49], v[48:49], v[62:63] op_sel_hi:[1,0]
	v_add_f32_dpp v34, v34, v34 row_ror:4 row_mask:0xf bank_mask:0xf bound_ctrl:1
	v_pk_fma_f32 v[48:49], v[24:25], v[44:45], v[48:49]
	s_nop 0
	v_add_f32_dpp v34, v34, v34 row_ror:8 row_mask:0xf bank_mask:0xf bound_ctrl:1
	v_pk_fma_f32 v[22:23], v[54:55], v[34:35], v[46:47] op_sel_hi:[1,0,1]
	v_pk_fma_f32 v[24:25], v[56:57], v[34:35], v[48:49] op_sel_hi:[1,0,1]
	v_pk_mul_f32 v[66:67], v[22:23], v[58:59]
	v_pk_fma_f32 v[66:67], v[24:25], v[60:61], v[66:67]
	v_add_f32_e32 v66, v66, v67
	s_nop 1
	v_add_f32_dpp v66, v66, v66 row_ror:1 row_mask:0xf bank_mask:0xf bound_ctrl:1
	s_nop 1
	v_add_f32_dpp v66, v66, v66 row_ror:2 row_mask:0xf bank_mask:0xf bound_ctrl:1
	ds_write2st64_b32 v41, v36, v66 offset0:30 offset1:31
	s_add_i32 s14, s14, 1
	s_cmpk_eq_i32 s14, 0x100
	s_waitcnt lgkmcnt(0)
	s_barrier
	s_cbranch_scc0 .LBB0_1090
	s_setprio 0
	s_mov_b64 s[44:45], 0
